# attnB loop: V fragment refill reads moved out of the first four MFMA gaps after the barrier
# speedup vs baseline: 1.0159x; 1.0010x over previous
.Lb_loop:
	s_waitcnt lgkmcnt(0)
	v_mfma_f32_32x32x16_bf16 v[32:47], v[192:195], v[224:227], v[32:47]
	ds_read_b128 v[96:99], v146 offset:33280
	ds_read_b128 v[100:103], v147 offset:33280
	ds_read_b128 v[104:107], v148 offset:33280
	ds_read_b128 v[108:111], v149 offset:33280
	v_mfma_f32_32x32x16_bf16 v[48:63], v[196:199], v[224:227], v[48:63]
	v_mfma_f32_32x32x16_bf16 v[16:31], v[200:203], v[224:227], v[16:31]
	v_exp_f32_e32 v240, v80
	v_exp_f32_e32 v241, v81
	v_exp_f32_e32 v242, v82
	v_mfma_f32_32x32x16_bf16 v[0:15], v[204:207], v[224:227], v[0:15]
	v_exp_f32_e32 v243, v83
	v_exp_f32_e32 v244, v84
	v_exp_f32_e32 v245, v85
	s_waitcnt lgkmcnt(0)
	v_mfma_f32_32x32x16_bf16 v[112:127], v[96:99], v[128:131], v[64:79]
	ds_read_b128 v[96:99], v146 offset:37376
	ds_read_b64_tr_b16 v[192:193], v179 offset:18688
	ds_read_b64_tr_b16 v[194:195], v179 offset:19200
	v_add_f32_e32 v145, v240, v241
	v_cvt_pk_bf16_f32 v232, v240, v241
	v_exp_f32_e32 v246, v86
	v_exp_f32_e32 v247, v87
	v_mfma_f32_32x32x16_bf16 v[112:127], v[100:103], v[132:135], v[112:127]
	ds_read_b128 v[100:103], v147 offset:37376
	ds_read_b64_tr_b16 v[196:197], v179 offset:22848
	ds_read_b64_tr_b16 v[198:199], v179 offset:23360
	s_add_i32 s0, s50, 0xffff8000
	s_and_b32 s0, s0, 0x1f8000
	s_lshl_b32 s4, s0, 1
	s_add_i32 m0, s41, 0x18600
	s_nop 0
	buffer_load_dwordx4 v250, s[8:11], s4 offen lds
	s_add_i32 m0, s41, 0x1a600
	s_nop 0
	buffer_load_dwordx4 v250, s[8:11], s4 offen offset:128 lds
	v_add_f32_e32 v145, v145, v242
	v_add_f32_e32 v145, v145, v243
	v_cvt_pk_bf16_f32 v233, v242, v243
	v_exp_f32_e32 v240, v88
	v_mfma_f32_32x32x16_bf16 v[112:127], v[104:107], v[136:139], v[112:127]
	ds_read_b128 v[104:107], v148 offset:37376
	ds_read_b64_tr_b16 v[200:201], v179 offset:27008
	ds_read_b64_tr_b16 v[202:203], v179 offset:27520
	v_exp_f32_e32 v241, v89
	v_add_f32_e32 v145, v145, v244
	v_add_f32_e32 v145, v145, v245
	v_cvt_pk_bf16_f32 v234, v244, v245
	v_exp_f32_e32 v242, v90
	v_mfma_f32_32x32x16_bf16 v[112:127], v[108:111], v[140:143], v[112:127]
	ds_read_b128 v[108:111], v149 offset:37376
	ds_read_b64_tr_b16 v[204:205], v179 offset:31168
	ds_read_b64_tr_b16 v[206:207], v179 offset:31680
	s_add_i32 m0, s43, 0x18600
	s_nop 0
	buffer_load_dwordx4 v251, s[12:15], s4 offen lds
	s_add_i32 m0, s43, 0x1a600
	s_nop 0
	buffer_load_dwordx4 v251, s[12:15], s4 offen offset:128 lds
	v_exp_f32_e32 v243, v91
	v_add_f32_e32 v145, v145, v246
	v_add_f32_e32 v145, v145, v247
	v_cvt_pk_bf16_f32 v235, v246, v247
	v_mfma_f32_32x32x16_bf16 v[32:47], v[208:211], v[228:231], v[32:47]
	ds_read_b64_tr_b16 v[208:209], v179 offset:19712
	ds_read_b64_tr_b16 v[210:211], v179 offset:20224
	v_exp_f32_e32 v244, v92
	v_exp_f32_e32 v245, v93
	v_add_f32_e32 v145, v145, v240
	v_add_f32_e32 v145, v145, v241
	v_mfma_f32_32x32x16_bf16 v[48:63], v[212:215], v[228:231], v[48:63]
	ds_read_b64_tr_b16 v[212:213], v179 offset:23872
	ds_read_b64_tr_b16 v[214:215], v179 offset:24384
	v_cvt_pk_bf16_f32 v236, v240, v241
	v_exp_f32_e32 v246, v94
	v_exp_f32_e32 v247, v95
	v_mfma_f32_32x32x16_bf16 v[16:31], v[216:219], v[228:231], v[16:31]
	ds_read_b64_tr_b16 v[216:217], v179 offset:28032
	ds_read_b64_tr_b16 v[218:219], v179 offset:28544
	v_add_f32_e32 v145, v145, v242
	v_add_f32_e32 v145, v145, v243
	v_cvt_pk_bf16_f32 v237, v242, v243
	v_add_f32_e32 v145, v145, v244
	v_add_f32_e32 v145, v145, v245
	v_cvt_pk_bf16_f32 v238, v244, v245
	v_mfma_f32_32x32x16_bf16 v[0:15], v[220:223], v[228:231], v[0:15]
	ds_read_b64_tr_b16 v[220:221], v179 offset:32192
	ds_read_b64_tr_b16 v[222:223], v179 offset:32704
	v_add_f32_e32 v145, v145, v246
	v_add_f32_e32 v249, v145, v247
	v_cvt_pk_bf16_f32 v239, v246, v247
	v_add_f32_e32 v249, v248, v249
	v_cmp_lt_f32_e32 vcc, s3, v249
	v_add_f32_e32 v191, v191, v249
	s_waitcnt lgkmcnt(8)
	v_mfma_f32_32x32x16_bf16 v[80:95], v[96:99], v[128:131], v[64:79]
	v_exp_f32_e32 v240, v112
	v_exp_f32_e32 v241, v113
	v_mfma_f32_32x32x16_bf16 v[80:95], v[100:103], v[132:135], v[80:95]
	v_exp_f32_e32 v242, v114
	v_exp_f32_e32 v243, v115
	v_exp_f32_e32 v244, v116
	v_mfma_f32_32x32x16_bf16 v[80:95], v[104:107], v[136:139], v[80:95]
	v_exp_f32_e32 v245, v117
	v_add_f32_e32 v145, v240, v241
	v_cvt_pk_bf16_f32 v224, v240, v241
	v_mfma_f32_32x32x16_bf16 v[80:95], v[108:111], v[140:143], v[80:95]
	v_exp_f32_e32 v246, v118
	v_exp_f32_e32 v247, v119
	v_mfma_f32_32x32x16_bf16 v[32:47], v[192:195], v[232:235], v[32:47]
	ds_read_b64_tr_b16 v[192:193], v180 offset:0
	ds_read_b64_tr_b16 v[194:195], v180 offset:512
	v_add_f32_e32 v145, v145, v242
	v_add_f32_e32 v145, v145, v243
	v_cvt_pk_bf16_f32 v225, v242, v243
	v_exp_f32_e32 v240, v120
	v_mfma_f32_32x32x16_bf16 v[48:63], v[196:199], v[232:235], v[48:63]
	ds_read_b64_tr_b16 v[196:197], v180 offset:4160
	ds_read_b64_tr_b16 v[198:199], v180 offset:4672
	v_exp_f32_e32 v241, v121
	v_add_f32_e32 v145, v145, v244
	v_add_f32_e32 v145, v145, v245
	v_cvt_pk_bf16_f32 v226, v244, v245
	v_mfma_f32_32x32x16_bf16 v[16:31], v[200:203], v[232:235], v[16:31]
	ds_read_b64_tr_b16 v[200:201], v180 offset:8320
	ds_read_b64_tr_b16 v[202:203], v180 offset:8832
	v_exp_f32_e32 v242, v122
	v_exp_f32_e32 v243, v123
	v_mfma_f32_32x32x16_bf16 v[0:15], v[204:207], v[232:235], v[0:15]
	ds_read_b64_tr_b16 v[204:205], v180 offset:12480
	ds_read_b64_tr_b16 v[206:207], v180 offset:12992
	v_add_f32_e32 v145, v145, v246
	v_add_f32_e32 v145, v145, v247
	v_cvt_pk_bf16_f32 v227, v246, v247
	v_exp_f32_e32 v244, v124
	s_waitcnt lgkmcnt(8)
	v_mfma_f32_32x32x16_bf16 v[32:47], v[208:211], v[236:239], v[32:47]
	ds_read_b64_tr_b16 v[208:209], v180 offset:1024
	ds_read_b64_tr_b16 v[210:211], v180 offset:1536
	v_exp_f32_e32 v245, v125
	v_add_f32_e32 v145, v145, v240
	v_add_f32_e32 v145, v145, v241
	v_mfma_f32_32x32x16_bf16 v[48:63], v[212:215], v[236:239], v[48:63]
	ds_read_b64_tr_b16 v[212:213], v180 offset:5184
	ds_read_b64_tr_b16 v[214:215], v180 offset:5696
	v_cvt_pk_bf16_f32 v228, v240, v241
	v_exp_f32_e32 v246, v126
	v_exp_f32_e32 v247, v127
	v_mfma_f32_32x32x16_bf16 v[16:31], v[216:219], v[236:239], v[16:31]
	ds_read_b64_tr_b16 v[216:217], v180 offset:9344
	ds_read_b64_tr_b16 v[218:219], v180 offset:9856
	v_add_f32_e32 v145, v145, v242
	v_add_f32_e32 v145, v145, v243
	v_cvt_pk_bf16_f32 v229, v242, v243
	v_add_f32_e32 v145, v145, v244
	v_mfma_f32_32x32x16_bf16 v[0:15], v[220:223], v[236:239], v[0:15]
	ds_read_b64_tr_b16 v[220:221], v180 offset:13504
	ds_read_b64_tr_b16 v[222:223], v180 offset:14016
	v_add_f32_e32 v145, v145, v245
	v_cvt_pk_bf16_f32 v230, v244, v245
	v_add_f32_e32 v145, v145, v246
	v_add_f32_e32 v248, v145, v247
	v_cvt_pk_bf16_f32 v231, v246, v247
	s_cbranch_vccz .Lb_cont0
	s_branch .Lb_rare0
.Lb_cont0:
	s_waitcnt vmcnt(4)
	s_barrier
	s_waitcnt lgkmcnt(0)
	v_mfma_f32_32x32x16_bf16 v[32:47], v[192:195], v[224:227], v[32:47]
	ds_read_b128 v[96:99], v150 offset:0
	ds_read_b128 v[100:103], v151 offset:0
	ds_read_b128 v[104:107], v152 offset:0
	ds_read_b128 v[108:111], v153 offset:0
	v_mfma_f32_32x32x16_bf16 v[48:63], v[196:199], v[224:227], v[48:63]
	v_mfma_f32_32x32x16_bf16 v[16:31], v[200:203], v[224:227], v[16:31]
	v_exp_f32_e32 v240, v80
	v_exp_f32_e32 v241, v81
	v_exp_f32_e32 v242, v82
	v_mfma_f32_32x32x16_bf16 v[0:15], v[204:207], v[224:227], v[0:15]
	v_exp_f32_e32 v243, v83
	v_exp_f32_e32 v244, v84
	v_exp_f32_e32 v245, v85
	s_waitcnt lgkmcnt(0)
	v_mfma_f32_32x32x16_bf16 v[112:127], v[96:99], v[128:131], v[64:79]
	ds_read_b128 v[96:99], v150 offset:4096
	ds_read_b64_tr_b16 v[192:193], v180 offset:2048
	ds_read_b64_tr_b16 v[194:195], v180 offset:2560
	v_add_f32_e32 v145, v240, v241
	v_cvt_pk_bf16_f32 v232, v240, v241
	v_exp_f32_e32 v246, v86
	v_exp_f32_e32 v247, v87
	v_mfma_f32_32x32x16_bf16 v[112:127], v[100:103], v[132:135], v[112:127]
	ds_read_b128 v[100:103], v151 offset:4096
	ds_read_b64_tr_b16 v[196:197], v180 offset:6208
	ds_read_b64_tr_b16 v[198:199], v180 offset:6720
	s_cmp_gt_u32 s6, 59
	s_cbranch_scc1 .Lb_pn0
	s_and_b32 s0, s50, 0x1f8000
	s_lshl_b32 s4, s0, 1
	s_add_i32 m0, s41, 0x0
	s_nop 0
	buffer_load_dwordx4 v250, s[8:11], s4 offen lds
	s_branch .Lb_po0

.Lb_po0:
	s_cmp_gt_u32 s6, 59
	s_cbranch_scc1 .Lb_pn1
	s_add_i32 m0, s41, 0x2000
	s_nop 0
	buffer_load_dwordx4 v250, s[8:11], s4 offen offset:128 lds
.Lb_pn1:
	v_add_f32_e32 v145, v145, v242
	v_add_f32_e32 v145, v145, v243
	v_cvt_pk_bf16_f32 v233, v242, v243
	v_exp_f32_e32 v240, v88
	v_mfma_f32_32x32x16_bf16 v[112:127], v[104:107], v[136:139], v[112:127]
	ds_read_b128 v[104:107], v152 offset:4096
	ds_read_b64_tr_b16 v[200:201], v180 offset:10368
	ds_read_b64_tr_b16 v[202:203], v180 offset:10880
	v_exp_f32_e32 v241, v89
	v_add_f32_e32 v145, v145, v244
	v_add_f32_e32 v145, v145, v245
	v_cvt_pk_bf16_f32 v234, v244, v245
	v_exp_f32_e32 v242, v90
	v_mfma_f32_32x32x16_bf16 v[112:127], v[108:111], v[140:143], v[112:127]
	ds_read_b128 v[108:111], v153 offset:4096
	ds_read_b64_tr_b16 v[204:205], v180 offset:14528
	ds_read_b64_tr_b16 v[206:207], v180 offset:15040
	s_cmp_gt_u32 s6, 59
	s_cbranch_scc1 .Lb_pn2
	s_add_i32 m0, s43, 0x0
	s_nop 0
	buffer_load_dwordx4 v251, s[12:15], s4 offen lds
.Lb_pn2:
	s_cmp_gt_u32 s6, 59
	s_cbranch_scc1 .Lb_pn3
	s_add_i32 m0, s43, 0x2000
	s_nop 0
	buffer_load_dwordx4 v251, s[12:15], s4 offen offset:128 lds

.Lb_cont1:
	s_waitcnt vmcnt(4)
	s_barrier
	s_waitcnt lgkmcnt(0)
	v_mfma_f32_32x32x16_bf16 v[32:47], v[192:195], v[224:227], v[32:47]
	ds_read_b128 v[96:99], v150 offset:33280
	ds_read_b128 v[100:103], v151 offset:33280
	ds_read_b128 v[104:107], v152 offset:33280
	ds_read_b128 v[108:111], v153 offset:33280
	v_mfma_f32_32x32x16_bf16 v[48:63], v[196:199], v[224:227], v[48:63]
	v_mfma_f32_32x32x16_bf16 v[16:31], v[200:203], v[224:227], v[16:31]
	v_exp_f32_e32 v240, v80
	v_exp_f32_e32 v241, v81
	v_exp_f32_e32 v242, v82
	v_mfma_f32_32x32x16_bf16 v[0:15], v[204:207], v[224:227], v[0:15]
	v_exp_f32_e32 v243, v83
	v_exp_f32_e32 v244, v84
	v_exp_f32_e32 v245, v85
	s_waitcnt lgkmcnt(0)
	v_mfma_f32_32x32x16_bf16 v[112:127], v[96:99], v[128:131], v[64:79]
	ds_read_b128 v[96:99], v150 offset:37376
	ds_read_b64_tr_b16 v[192:193], v182 offset:2048
	ds_read_b64_tr_b16 v[194:195], v182 offset:2560
	v_add_f32_e32 v145, v240, v241
	v_cvt_pk_bf16_f32 v232, v240, v241
	v_exp_f32_e32 v246, v86
	v_exp_f32_e32 v247, v87
	v_mfma_f32_32x32x16_bf16 v[112:127], v[100:103], v[132:135], v[112:127]
	ds_read_b128 v[100:103], v151 offset:37376
	ds_read_b64_tr_b16 v[196:197], v182 offset:6208
	ds_read_b64_tr_b16 v[198:199], v182 offset:6720
	s_cmp_gt_u32 s6, 59
	s_cbranch_scc1 .Lb_pn4
	s_add_i32 s0, s50, 0x8000
	s_and_b32 s0, s0, 0x1f8000
	s_lshl_b32 s4, s0, 1
	s_add_i32 m0, s41, 0x8200
	s_nop 0
	buffer_load_dwordx4 v250, s[8:11], s4 offen lds
	s_branch .Lb_po4

.Lb_po4:
	s_cmp_gt_u32 s6, 59
	s_cbranch_scc1 .Lb_pn5
	s_add_i32 m0, s41, 0xa200
	s_nop 0
	buffer_load_dwordx4 v250, s[8:11], s4 offen offset:128 lds
.Lb_pn5:
	v_add_f32_e32 v145, v145, v242
	v_add_f32_e32 v145, v145, v243
	v_cvt_pk_bf16_f32 v233, v242, v243
	v_exp_f32_e32 v240, v88
	v_mfma_f32_32x32x16_bf16 v[112:127], v[104:107], v[136:139], v[112:127]
	ds_read_b128 v[104:107], v152 offset:37376
	ds_read_b64_tr_b16 v[200:201], v182 offset:10368
	ds_read_b64_tr_b16 v[202:203], v182 offset:10880
	v_exp_f32_e32 v241, v89
	v_add_f32_e32 v145, v145, v244
	v_add_f32_e32 v145, v145, v245
	v_cvt_pk_bf16_f32 v234, v244, v245
	v_exp_f32_e32 v242, v90
	v_mfma_f32_32x32x16_bf16 v[112:127], v[108:111], v[140:143], v[112:127]
	ds_read_b128 v[108:111], v153 offset:37376
	ds_read_b64_tr_b16 v[204:205], v182 offset:14528
	ds_read_b64_tr_b16 v[206:207], v182 offset:15040
	s_cmp_gt_u32 s6, 59
	s_cbranch_scc1 .Lb_pn6
	s_add_i32 m0, s43, 0x8200
	s_nop 0
	buffer_load_dwordx4 v251, s[12:15], s4 offen lds
.Lb_pn6:
	s_cmp_gt_u32 s6, 59
	s_cbranch_scc1 .Lb_pn7
	s_add_i32 m0, s43, 0xa200
	s_nop 0
	buffer_load_dwordx4 v251, s[12:15], s4 offen offset:128 lds

.Lb_cont2:
	s_waitcnt vmcnt(4)
	s_barrier
	s_cmp_gt_u32 s6, 59
	s_cbranch_scc1 .Lb_final
	s_waitcnt lgkmcnt(0)
	v_mfma_f32_32x32x16_bf16 v[32:47], v[192:195], v[224:227], v[32:47]
	ds_read_b128 v[96:99], v146 offset:0
	ds_read_b128 v[100:103], v147 offset:0
	ds_read_b128 v[104:107], v148 offset:0
	ds_read_b128 v[108:111], v149 offset:0
	v_mfma_f32_32x32x16_bf16 v[48:63], v[196:199], v[224:227], v[48:63]
	v_mfma_f32_32x32x16_bf16 v[16:31], v[200:203], v[224:227], v[16:31]
	v_exp_f32_e32 v240, v80
	v_exp_f32_e32 v241, v81
	v_exp_f32_e32 v242, v82
	v_mfma_f32_32x32x16_bf16 v[0:15], v[204:207], v[224:227], v[0:15]
	v_exp_f32_e32 v243, v83
	v_exp_f32_e32 v244, v84
	v_exp_f32_e32 v245, v85
	s_waitcnt lgkmcnt(0)
	v_mfma_f32_32x32x16_bf16 v[112:127], v[96:99], v[128:131], v[64:79]
	ds_read_b128 v[96:99], v146 offset:4096
	ds_read_b64_tr_b16 v[192:193], v182 offset:35328
	ds_read_b64_tr_b16 v[194:195], v182 offset:35840
	v_add_f32_e32 v145, v240, v241
	v_cvt_pk_bf16_f32 v232, v240, v241
	v_exp_f32_e32 v246, v86
	v_exp_f32_e32 v247, v87
	v_mfma_f32_32x32x16_bf16 v[112:127], v[100:103], v[132:135], v[112:127]
	ds_read_b128 v[100:103], v147 offset:4096
	ds_read_b64_tr_b16 v[196:197], v182 offset:39488
	ds_read_b64_tr_b16 v[198:199], v182 offset:40000
	s_add_i32 s0, s50, 0x10000
	s_and_b32 s0, s0, 0x1f8000
	s_lshl_b32 s4, s0, 1
	s_add_i32 m0, s41, 0x10400
	s_nop 0
	buffer_load_dwordx4 v250, s[8:11], s4 offen lds
	s_add_i32 m0, s41, 0x12400
	s_nop 0
	buffer_load_dwordx4 v250, s[8:11], s4 offen offset:128 lds
	v_add_f32_e32 v145, v145, v242
	v_add_f32_e32 v145, v145, v243
	v_cvt_pk_bf16_f32 v233, v242, v243
	v_exp_f32_e32 v240, v88
	v_mfma_f32_32x32x16_bf16 v[112:127], v[104:107], v[136:139], v[112:127]
	ds_read_b128 v[104:107], v148 offset:4096
	ds_read_b64_tr_b16 v[200:201], v182 offset:43648
	ds_read_b64_tr_b16 v[202:203], v182 offset:44160
	v_exp_f32_e32 v241, v89
	v_add_f32_e32 v145, v145, v244
	v_add_f32_e32 v145, v145, v245
	v_cvt_pk_bf16_f32 v234, v244, v245
	v_exp_f32_e32 v242, v90
	v_mfma_f32_32x32x16_bf16 v[112:127], v[108:111], v[140:143], v[112:127]
	ds_read_b128 v[108:111], v149 offset:4096
	ds_read_b64_tr_b16 v[204:205], v182 offset:47808
	ds_read_b64_tr_b16 v[206:207], v182 offset:48320
	s_add_i32 m0, s43, 0x10400
	s_nop 0
	buffer_load_dwordx4 v251, s[12:15], s4 offen lds
	s_add_i32 m0, s43, 0x12400
	s_nop 0
	buffer_load_dwordx4 v251, s[12:15], s4 offen offset:128 lds
	v_exp_f32_e32 v243, v91
	v_add_f32_e32 v145, v145, v246
	v_add_f32_e32 v145, v145, v247
	v_cvt_pk_bf16_f32 v235, v246, v247
	v_mfma_f32_32x32x16_bf16 v[32:47], v[208:211], v[228:231], v[32:47]
	ds_read_b64_tr_b16 v[208:209], v182 offset:36352
	ds_read_b64_tr_b16 v[210:211], v182 offset:36864
	v_exp_f32_e32 v244, v92
	v_exp_f32_e32 v245, v93
	v_add_f32_e32 v145, v145, v240
	v_add_f32_e32 v145, v145, v241
	v_mfma_f32_32x32x16_bf16 v[48:63], v[212:215], v[228:231], v[48:63]
	ds_read_b64_tr_b16 v[212:213], v182 offset:40512
	ds_read_b64_tr_b16 v[214:215], v182 offset:41024
	v_cvt_pk_bf16_f32 v236, v240, v241
	v_exp_f32_e32 v246, v94
	v_exp_f32_e32 v247, v95
	v_mfma_f32_32x32x16_bf16 v[16:31], v[216:219], v[228:231], v[16:31]
	ds_read_b64_tr_b16 v[216:217], v182 offset:44672
	ds_read_b64_tr_b16 v[218:219], v182 offset:45184
	v_add_f32_e32 v145, v145, v242
	v_add_f32_e32 v145, v145, v243
	v_cvt_pk_bf16_f32 v237, v242, v243
	v_add_f32_e32 v145, v145, v244
	v_add_f32_e32 v145, v145, v245
	v_cvt_pk_bf16_f32 v238, v244, v245
	v_mfma_f32_32x32x16_bf16 v[0:15], v[220:223], v[228:231], v[0:15]
	ds_read_b64_tr_b16 v[220:221], v182 offset:48832
	ds_read_b64_tr_b16 v[222:223], v182 offset:49344
	v_add_f32_e32 v145, v145, v246
	v_add_f32_e32 v249, v145, v247
	v_cvt_pk_bf16_f32 v239, v246, v247
	v_add_f32_e32 v249, v248, v249
	v_cmp_lt_f32_e32 vcc, s3, v249
	v_add_f32_e32 v191, v191, v249
	s_waitcnt lgkmcnt(8)
	v_mfma_f32_32x32x16_bf16 v[80:95], v[96:99], v[128:131], v[64:79]
	v_exp_f32_e32 v240, v112
	v_exp_f32_e32 v241, v113
	v_mfma_f32_32x32x16_bf16 v[80:95], v[100:103], v[132:135], v[80:95]
	v_exp_f32_e32 v242, v114
	v_exp_f32_e32 v243, v115
	v_exp_f32_e32 v244, v116
	v_mfma_f32_32x32x16_bf16 v[80:95], v[104:107], v[136:139], v[80:95]
	v_exp_f32_e32 v245, v117
	v_add_f32_e32 v145, v240, v241
	v_cvt_pk_bf16_f32 v224, v240, v241
	v_mfma_f32_32x32x16_bf16 v[80:95], v[108:111], v[140:143], v[80:95]
	v_exp_f32_e32 v246, v118
	v_exp_f32_e32 v247, v119
	v_mfma_f32_32x32x16_bf16 v[32:47], v[192:195], v[232:235], v[32:47]
	ds_read_b64_tr_b16 v[192:193], v179 offset:16640
	ds_read_b64_tr_b16 v[194:195], v179 offset:17152
	v_add_f32_e32 v145, v145, v242
	v_add_f32_e32 v145, v145, v243
	v_cvt_pk_bf16_f32 v225, v242, v243
	v_exp_f32_e32 v240, v120
	v_mfma_f32_32x32x16_bf16 v[48:63], v[196:199], v[232:235], v[48:63]
	ds_read_b64_tr_b16 v[196:197], v179 offset:20800
	ds_read_b64_tr_b16 v[198:199], v179 offset:21312
	v_exp_f32_e32 v241, v121
	v_add_f32_e32 v145, v145, v244
	v_add_f32_e32 v145, v145, v245
	v_cvt_pk_bf16_f32 v226, v244, v245
	v_mfma_f32_32x32x16_bf16 v[16:31], v[200:203], v[232:235], v[16:31]
	ds_read_b64_tr_b16 v[200:201], v179 offset:24960
	ds_read_b64_tr_b16 v[202:203], v179 offset:25472
	v_exp_f32_e32 v242, v122
	v_exp_f32_e32 v243, v123
	v_mfma_f32_32x32x16_bf16 v[0:15], v[204:207], v[232:235], v[0:15]
	ds_read_b64_tr_b16 v[204:205], v179 offset:29120
	ds_read_b64_tr_b16 v[206:207], v179 offset:29632
	v_add_f32_e32 v145, v145, v246
	v_add_f32_e32 v145, v145, v247
	v_cvt_pk_bf16_f32 v227, v246, v247
	v_exp_f32_e32 v244, v124
	s_waitcnt lgkmcnt(8)
	v_mfma_f32_32x32x16_bf16 v[32:47], v[208:211], v[236:239], v[32:47]
	ds_read_b64_tr_b16 v[208:209], v179 offset:17664
	ds_read_b64_tr_b16 v[210:211], v179 offset:18176
	v_exp_f32_e32 v245, v125
	v_add_f32_e32 v145, v145, v240
	v_add_f32_e32 v145, v145, v241
	v_mfma_f32_32x32x16_bf16 v[48:63], v[212:215], v[236:239], v[48:63]
	ds_read_b64_tr_b16 v[212:213], v179 offset:21824
	ds_read_b64_tr_b16 v[214:215], v179 offset:22336
	v_cvt_pk_bf16_f32 v228, v240, v241
	v_exp_f32_e32 v246, v126
	v_exp_f32_e32 v247, v127
	v_mfma_f32_32x32x16_bf16 v[16:31], v[216:219], v[236:239], v[16:31]
	ds_read_b64_tr_b16 v[216:217], v179 offset:25984
	ds_read_b64_tr_b16 v[218:219], v179 offset:26496
	v_add_f32_e32 v145, v145, v242
	v_add_f32_e32 v145, v145, v243
	v_cvt_pk_bf16_f32 v229, v242, v243
	v_add_f32_e32 v145, v145, v244
	v_mfma_f32_32x32x16_bf16 v[0:15], v[220:223], v[236:239], v[0:15]
	ds_read_b64_tr_b16 v[220:221], v179 offset:30144
	ds_read_b64_tr_b16 v[222:223], v179 offset:30656
	v_add_f32_e32 v145, v145, v245
	v_cvt_pk_bf16_f32 v230, v244, v245
	v_add_f32_e32 v145, v145, v246
	v_add_f32_e32 v248, v145, v247
	v_cvt_pk_bf16_f32 v231, v246, v247
	s_cbranch_vccz .Lb_cont3
	s_branch .Lb_rare3
